# speedup vs baseline: 1.0059x; 1.0059x over previous
.LBB0_140:
	v_lshl_add_u64 v[2:3], v[156:157], 0, v[142:143]
	s_mov_b64 s[58:59], 0x30e50080
	v_lshl_add_u64 v[28:29], v[2:3], 0, s[58:59]
	v_lshl_add_u64 v[20:21], v[158:159], 0, v[142:143]
	s_mov_b64 s[58:59], 0x2f570000
	v_lshl_add_u64 v[22:23], v[20:21], 0, s[58:59]
	s_mov_b32 s58, 0x2f570000
	v_add_co_u32_e32 v20, vcc, s58, v20
	s_mov_b32 s58, 0x30e50000
	s_nop 0
	v_addc_co_u32_e32 v21, vcc, 0, v21, vcc
	v_add_co_u32_e32 v2, vcc, s58, v2
	global_load_dwordx4 v[24:27], v[20:21], off
	s_nop 0
	global_load_dwordx4 v[20:23], v[22:23], off offset:16
	v_addc_co_u32_e32 v3, vcc, 0, v3, vcc
	global_load_dwordx4 v[32:35], v[2:3], off offset:128
	s_nop 0
	global_load_dwordx4 v[28:31], v[28:29], off offset:16
	s_and_b32 s58, 1, s31
	s_cselect_b32 s59, 0, 0x8800
	s_add_i32 s59, s59, 0
	v_add_u32_e32 v0, s59, v169
	v_add_u32_e32 v199, v0, v166
	ds_read_b128 v[100:103], v199
	v_add_u32_e32 v192, v0, v167
	ds_read_b128 v[104:107], v192
	ds_read_b128 v[108:111], v199 offset:4096
	ds_read_b128 v[112:115], v192 offset:4096
	s_waitcnt vmcnt(5) lgkmcnt(1)
	v_mfma_f32_16x16x32_bf16 v[116:119], v[108:111], v[16:19], 0
	v_add_u32_e32 v2, s59, v162
	v_add_u32_e32 v189, v2, v155
	v_add_u32_e32 v193, v0, v168
	v_mfma_f32_16x16x32_bf16 v[100:103], v[100:103], v[16:19], 0
	v_add_u32_e32 v160, v0, v165
	ds_read_b128 v[120:123], v193
	ds_read_b128 v[136:139], v193 offset:4096
	ds_read_b128 v[124:127], v160
	ds_read_b128 v[224:227], v160 offset:4096
	v_add_u32_e32 v194, 0x4000, v189
	s_waitcnt lgkmcnt(4)
	v_mfma_f32_16x16x32_bf16 v[128:131], v[112:115], v[12:15], v[116:119]
	v_add_u32_e32 v196, 0x4800, v189
	v_add_u32_e32 v198, 0x5000, v189
	v_add_u32_e32 v195, 0x5800, v189
	v_mfma_f32_16x16x32_bf16 v[100:103], v[104:107], v[12:15], v[100:103]
	v_add_u32_e32 v201, 0x6000, v189
	s_nop 2
	v_mul_f32_e32 v188, 0x3e38aa3b, v130
	v_mul_f32_e32 v2, 0x3e38aa3b, v131
	v_mul_f32_e32 v186, 0x3e38aa3b, v128
	v_mul_f32_e32 v187, 0x3e38aa3b, v129
	v_mul_f32_e32 v3, 0x3e38aa3b, v100
	v_mul_f32_e32 v172, 0x3e38aa3b, v101
	v_mul_f32_e32 v173, 0x3e38aa3b, v102
	v_mul_f32_e32 v185, 0x3e38aa3b, v103
	v_max_f32_e32 v101, v188, v2
	v_max_f32_e32 v0, v3, v172
	v_max_f32_e32 v100, v173, v185
	v_max3_f32 v101, v186, v187, v101
	v_max3_f32 v0, v0, v100, v101
	v_mov_b32_e32 v100, v0
	s_waitcnt lgkmcnt(3)
	v_mfma_f32_16x16x32_bf16 v[132:135], v[120:123], v[8:11], 0
	v_add_u32_e32 v202, 0x6800, v189
	v_add_u32_e32 v200, 0x7000, v189
	v_add_u32_e32 v205, 0x7800, v189
	s_waitcnt lgkmcnt(0)
	v_permlane16_swap_b32_e32 v100, v0
	v_max_f32_e32 v0, v0, v100
	v_mov_b32_e32 v100, v0
	v_mfma_f32_16x16x32_bf16 v[136:139], v[136:139], v[8:11], 0
	ds_read2_b64 v[104:107], v194 offset1:4
	ds_read2_b64 v[108:111], v196 offset0:32 offset1:36
	ds_read2_b64 v[112:115], v198 offset0:64 offset1:68
	s_waitcnt lgkmcnt(3)
	v_permlane32_swap_b32_e32 v100, v0
	v_max_f32_e32 v0, v0, v100
	v_add_f32_e32 v100, 0x41000000, v171
	v_cmp_gt_f32_e32 vcc, v0, v100
	s_cmp_eq_u64 vcc, 0
	v_max_f32_e32 v100, v171, v171
	v_max_f32_e32 v0, v100, v0
	s_cselect_b64 vcc, -1, 0
	v_cndmask_b32_e32 v203, v0, v171, vcc
	v_sub_f32_e32 v0, v171, v203
	ds_read2_b64 v[116:119], v195 offset0:96 offset1:100
	ds_read2_b64 v[120:123], v201 offset0:128 offset1:132
	s_waitcnt vmcnt(4)
	v_mfma_f32_16x16x32_bf16 v[132:135], v[124:127], v[4:7], v[132:135]
	ds_read2_b64 v[128:131], v202 offset0:160 offset1:164
	ds_read2_b64 v[124:127], v200 offset0:192 offset1:196
	v_exp_f32_e32 v0, v0
	ds_read2_b64 v[100:103], v205 offset0:224 offset1:228
	v_mfma_f32_16x16x32_bf16 v[136:139], v[224:227], v[4:7], v[136:139]
	v_cmp_neq_f32_e32 vcc, 1.0, v0
	s_cbranch_vccz .LBB0_142
	v_pk_mul_f32 v[78:79], v[78:79], v[0:1] op_sel_hi:[1,0]
	v_pk_mul_f32 v[76:77], v[76:77], v[0:1] op_sel_hi:[1,0]
	v_pk_mul_f32 v[74:75], v[74:75], v[0:1] op_sel_hi:[1,0]
	v_pk_mul_f32 v[72:73], v[72:73], v[0:1] op_sel_hi:[1,0]
	v_pk_mul_f32 v[66:67], v[66:67], v[0:1] op_sel_hi:[1,0]
	v_pk_mul_f32 v[64:65], v[64:65], v[0:1] op_sel_hi:[1,0]
	v_pk_mul_f32 v[62:63], v[62:63], v[0:1] op_sel_hi:[1,0]
	v_pk_mul_f32 v[60:61], v[60:61], v[0:1] op_sel_hi:[1,0]
	v_pk_mul_f32 v[58:59], v[58:59], v[0:1] op_sel_hi:[1,0]
	v_pk_mul_f32 v[56:57], v[56:57], v[0:1] op_sel_hi:[1,0]
	v_pk_mul_f32 v[54:55], v[54:55], v[0:1] op_sel_hi:[1,0]
	v_pk_mul_f32 v[52:53], v[52:53], v[0:1] op_sel_hi:[1,0]
	v_pk_mul_f32 v[50:51], v[50:51], v[0:1] op_sel_hi:[1,0]
	v_pk_mul_f32 v[48:49], v[48:49], v[0:1] op_sel_hi:[1,0]
	v_pk_mul_f32 v[42:43], v[42:43], v[0:1] op_sel_hi:[1,0]
	v_pk_mul_f32 v[40:41], v[40:41], v[0:1] op_sel_hi:[1,0]
.LBB0_142:
	v_sub_f32_e32 v171, v172, v203
	v_exp_f32_e32 v172, v171
	v_sub_f32_e32 v171, v173, v203
	v_exp_f32_e32 v173, v171
	v_sub_f32_e32 v171, v185, v203
	v_exp_f32_e32 v185, v171
	v_sub_f32_e32 v171, v186, v203
	v_exp_f32_e32 v186, v171
	v_sub_f32_e32 v171, v187, v203
	v_sub_f32_e32 v3, v3, v203
	v_exp_f32_e32 v187, v171
	v_sub_f32_e32 v171, v188, v203
	v_sub_f32_e32 v2, v2, v203
	v_exp_f32_e32 v3, v3
	v_exp_f32_e32 v188, v171
	v_exp_f32_e32 v189, v2
	v_cvt_pk_bf16_f32 v225, v173, v185
	v_cvt_pk_bf16_f32 v224, v3, v172
	v_cvt_pk_bf16_f32 v226, v186, v187
	v_cvt_pk_bf16_f32 v227, v188, v189
	v_mul_f32_e32 v171, 0x3e38aa3b, v135
	v_mul_f32_e32 v135, 0x3e38aa3b, v136
	s_waitcnt lgkmcnt(7)
	v_mfma_f32_16x16x32_bf16 v[76:79], v[104:107], v[224:227], v[76:79]
	s_waitcnt lgkmcnt(6)
	v_mfma_f32_16x16x32_bf16 v[72:75], v[108:111], v[224:227], v[72:75]
	s_waitcnt lgkmcnt(5)
	v_mfma_f32_16x16x32_bf16 v[64:67], v[112:115], v[224:227], v[64:67]
	s_waitcnt lgkmcnt(4)
	v_mfma_f32_16x16x32_bf16 v[60:63], v[116:119], v[224:227], v[60:63]
	s_waitcnt lgkmcnt(3)
	v_mfma_f32_16x16x32_bf16 v[56:59], v[120:123], v[224:227], v[56:59]
	s_waitcnt lgkmcnt(2)
	v_mfma_f32_16x16x32_bf16 v[52:55], v[128:131], v[224:227], v[52:55]
	s_waitcnt lgkmcnt(1)
	v_mfma_f32_16x16x32_bf16 v[48:51], v[124:127], v[224:227], v[48:51]
	s_waitcnt lgkmcnt(0)
	v_mfma_f32_16x16x32_bf16 v[40:43], v[100:103], v[224:227], v[40:43]
	v_mul_f32_e32 v224, 0x3e38aa3b, v132
	v_mul_f32_e32 v225, 0x3e38aa3b, v133
	v_mul_f32_e32 v133, 0x3e38aa3b, v138
	v_mul_f32_e32 v132, 0x3e38aa3b, v139
	v_mul_f32_e32 v226, 0x3e38aa3b, v134
	v_mul_f32_e32 v134, 0x3e38aa3b, v137
	v_max_f32_e32 v137, v133, v132
	v_max_f32_e32 v2, v224, v225
	v_max_f32_e32 v136, v226, v171
	v_max3_f32 v137, v135, v134, v137
	v_max3_f32 v2, v2, v136, v137
	v_mov_b32_e32 v136, v2
	s_nop 1
	v_permlane16_swap_b32_e32 v136, v2
	v_max_f32_e32 v2, v2, v136
	v_mov_b32_e32 v136, v2
	s_nop 1
	v_permlane32_swap_b32_e32 v136, v2
	v_max_f32_e32 v2, v2, v136
	v_add_f32_e32 v136, 0x41000000, v170
	v_cmp_gt_f32_e32 vcc, v2, v136
	s_cmp_eq_u64 vcc, 0
	v_max_f32_e32 v136, v170, v170
	s_cselect_b64 vcc, -1, 0
	v_max_f32_e32 v2, v136, v2
	v_cndmask_b32_e32 v204, v2, v170, vcc
	v_sub_f32_e32 v2, v170, v204
	v_exp_f32_e32 v2, v2
	s_nop 0
	v_cmp_neq_f32_e32 vcc, 1.0, v2
	s_cbranch_vccz .LBB0_144
	v_pk_mul_f32 v[46:47], v[46:47], v[2:3] op_sel_hi:[1,0]
	v_pk_mul_f32 v[44:45], v[44:45], v[2:3] op_sel_hi:[1,0]
	v_pk_mul_f32 v[70:71], v[70:71], v[2:3] op_sel_hi:[1,0]
	v_pk_mul_f32 v[68:69], v[68:69], v[2:3] op_sel_hi:[1,0]
	v_pk_mul_f32 v[82:83], v[82:83], v[2:3] op_sel_hi:[1,0]
	v_pk_mul_f32 v[80:81], v[80:81], v[2:3] op_sel_hi:[1,0]
	v_pk_mul_f32 v[86:87], v[86:87], v[2:3] op_sel_hi:[1,0]
	v_pk_mul_f32 v[84:85], v[84:85], v[2:3] op_sel_hi:[1,0]
	v_pk_mul_f32 v[90:91], v[90:91], v[2:3] op_sel_hi:[1,0]
	v_pk_mul_f32 v[88:89], v[88:89], v[2:3] op_sel_hi:[1,0]
	v_pk_mul_f32 v[94:95], v[94:95], v[2:3] op_sel_hi:[1,0]
	v_pk_mul_f32 v[92:93], v[92:93], v[2:3] op_sel_hi:[1,0]
	v_pk_mul_f32 v[98:99], v[98:99], v[2:3] op_sel_hi:[1,0]
	v_pk_mul_f32 v[96:97], v[96:97], v[2:3] op_sel_hi:[1,0]
	v_pk_mul_f32 v[38:39], v[38:39], v[2:3] op_sel_hi:[1,0]
	v_pk_mul_f32 v[36:37], v[36:37], v[2:3] op_sel_hi:[1,0]
.LBB0_144:
	v_sub_f32_e32 v136, v224, v204
	v_exp_f32_e32 v224, v136
	v_sub_f32_e32 v136, v225, v204
	v_exp_f32_e32 v225, v136
	v_sub_f32_e32 v136, v226, v204
	v_exp_f32_e32 v226, v136
	v_sub_f32_e32 v136, v171, v204
	v_sub_f32_e32 v135, v135, v204
	v_sub_f32_e32 v134, v134, v204
	v_sub_f32_e32 v133, v133, v204
	v_sub_f32_e32 v132, v132, v204
	v_exp_f32_e32 v227, v136
	v_exp_f32_e32 v228, v135
	v_exp_f32_e32 v229, v134
	v_exp_f32_e32 v230, v133
	v_exp_f32_e32 v231, v132
	v_cvt_pk_bf16_f32 v132, v224, v225
	v_cvt_pk_bf16_f32 v133, v226, v227
	v_cvt_pk_bf16_f32 v134, v228, v229
	v_cvt_pk_bf16_f32 v135, v230, v231
	s_nop 1
	v_mfma_f32_16x16x32_bf16 v[44:47], v[104:107], v[132:135], v[44:47]
	ds_read_b128 v[104:107], v199 offset:8192
	v_mfma_f32_16x16x32_bf16 v[68:71], v[108:111], v[132:135], v[68:71]
	v_mfma_f32_16x16x32_bf16 v[80:83], v[112:115], v[132:135], v[80:83]
	ds_read_b128 v[108:111], v192 offset:8192
	ds_read_b128 v[112:115], v199 offset:12288
	s_waitcnt lgkmcnt(2)
	v_mfma_f32_16x16x32_bf16 v[104:107], v[104:107], v[16:19], 0
	s_waitcnt lgkmcnt(1)
	v_mfma_f32_16x16x32_bf16 v[104:107], v[108:111], v[12:15], v[104:107]
	s_waitcnt lgkmcnt(0)
	v_mfma_f32_16x16x32_bf16 v[112:115], v[112:115], v[16:19], 0
	v_mfma_f32_16x16x32_bf16 v[84:87], v[116:119], v[132:135], v[84:87]
	s_nop 4
	v_mul_f32_e32 v235, 0x3e38aa3b, v106
	v_mul_f32_e32 v233, 0x3e38aa3b, v107
	v_mfma_f32_16x16x32_bf16 v[88:91], v[120:123], v[132:135], v[88:91]
	ds_read_b128 v[116:119], v192 offset:12288
	ds_read_b128 v[120:123], v193 offset:8192
	ds_read_b128 v[136:139], v193 offset:12288
	v_mul_f32_e32 v192, 0x3e38aa3b, v104
	v_mul_f32_e32 v193, 0x3e38aa3b, v105
	s_waitcnt lgkmcnt(2)
	v_mfma_f32_16x16x32_bf16 v[104:107], v[116:119], v[12:15], v[112:115]
	ds_read_b128 v[108:111], v160 offset:8192
	ds_read_b128 v[236:239], v160 offset:12288
	v_mfma_f32_16x16x32_bf16 v[36:39], v[100:103], v[132:135], v[36:39]
	s_nop 4
	v_mul_f32_e32 v170, 0x3e38aa3b, v106
	v_mul_f32_e32 v232, 0x3e38aa3b, v107
	v_mul_f32_e32 v234, 0x3e38aa3b, v104
	v_mul_f32_e32 v199, 0x3e38aa3b, v105
	v_max_f32_e32 v106, v170, v232
	v_max_f32_e32 v104, v192, v193
	v_max_f32_e32 v105, v235, v233
	v_max3_f32 v106, v234, v199, v106
	v_max3_f32 v104, v104, v105, v106
	v_mov_b32_e32 v105, v104
	s_waitcnt lgkmcnt(3)
	v_mfma_f32_16x16x32_bf16 v[100:103], v[120:123], v[8:11], 0
	v_mfma_f32_16x16x32_bf16 v[92:95], v[128:131], v[132:135], v[92:95]
	v_mfma_f32_16x16x32_bf16 v[96:99], v[124:127], v[132:135], v[96:99]
	ds_read2_b64 v[128:131], v194 offset0:8 offset1:12
	ds_read2_b64 v[124:127], v196 offset0:40 offset1:44
	ds_read2_b64 v[120:123], v198 offset0:72 offset1:76
	s_waitcnt lgkmcnt(4)
	v_mfma_f32_16x16x32_bf16 v[132:135], v[108:111], v[4:7], v[100:103]
	s_waitcnt lgkmcnt(3)
	s_nop 1
	v_permlane16_swap_b32_e32 v105, v104
	v_max_f32_e32 v100, v104, v105
	v_mov_b32_e32 v101, v100
	v_mfma_f32_16x16x32_bf16 v[136:139], v[136:139], v[8:11], 0
	ds_read2_b64 v[116:119], v195 offset0:104 offset1:108
	ds_read2_b64 v[112:115], v201 offset0:136 offset1:140
	ds_read2_b64 v[104:107], v202 offset0:168 offset1:172
	s_waitcnt lgkmcnt(3)
	v_permlane32_swap_b32_e32 v101, v100
	v_max_f32_e32 v100, v100, v101
	v_add_f32_e32 v101, 0x41000000, v203
	v_cmp_gt_f32_e32 vcc, v100, v101
	s_cmp_eq_u64 vcc, 0
	v_max_f32_e32 v101, v203, v203
	v_max_f32_e32 v100, v101, v100
	s_cselect_b64 vcc, -1, 0
	v_cndmask_b32_e32 v171, v100, v203, vcc
	v_sub_f32_e32 v100, v203, v171
	v_exp_f32_e32 v160, v100
	ds_read2_b64 v[108:111], v200 offset0:200 offset1:204
	ds_read2_b64 v[100:103], v205 offset0:232 offset1:236
	v_mfma_f32_16x16x32_bf16 v[136:139], v[236:239], v[4:7], v[136:139]
	v_cmp_neq_f32_e32 vcc, 1.0, v160
	s_cbranch_vccz .LBB0_146
	v_pk_mul_f32 v[78:79], v[78:79], v[160:161] op_sel_hi:[1,0]
	v_pk_mul_f32 v[76:77], v[76:77], v[160:161] op_sel_hi:[1,0]
	v_pk_mul_f32 v[74:75], v[74:75], v[160:161] op_sel_hi:[1,0]
	v_pk_mul_f32 v[72:73], v[72:73], v[160:161] op_sel_hi:[1,0]
	v_pk_mul_f32 v[66:67], v[66:67], v[160:161] op_sel_hi:[1,0]
	v_pk_mul_f32 v[64:65], v[64:65], v[160:161] op_sel_hi:[1,0]
	v_pk_mul_f32 v[62:63], v[62:63], v[160:161] op_sel_hi:[1,0]
	v_pk_mul_f32 v[60:61], v[60:61], v[160:161] op_sel_hi:[1,0]
	v_pk_mul_f32 v[58:59], v[58:59], v[160:161] op_sel_hi:[1,0]
	v_pk_mul_f32 v[56:57], v[56:57], v[160:161] op_sel_hi:[1,0]
	v_pk_mul_f32 v[54:55], v[54:55], v[160:161] op_sel_hi:[1,0]
	v_pk_mul_f32 v[52:53], v[52:53], v[160:161] op_sel_hi:[1,0]
	v_pk_mul_f32 v[50:51], v[50:51], v[160:161] op_sel_hi:[1,0]
	v_pk_mul_f32 v[48:49], v[48:49], v[160:161] op_sel_hi:[1,0]
	v_pk_mul_f32 v[42:43], v[42:43], v[160:161] op_sel_hi:[1,0]
	v_pk_mul_f32 v[40:41], v[40:41], v[160:161] op_sel_hi:[1,0]
.LBB0_146:
	v_mul_f32_e32 v203, 0x3e38aa3b, v133
	v_mul_f32_e32 v202, 0x3e38aa3b, v134
	v_mul_f32_e32 v134, 0x3e38aa3b, v138
	s_nop 2
	v_mul_f32_e32 v133, 0x3e38aa3b, v139
	v_mul_f32_e32 v205, 0x3e38aa3b, v132
	v_mul_f32_e32 v201, 0x3e38aa3b, v135
	v_mul_f32_e32 v136, 0x3e38aa3b, v136
	v_mul_f32_e32 v135, 0x3e38aa3b, v137
	v_max_f32_e32 v138, v134, v133
	v_max_f32_e32 v132, v205, v203
	v_max_f32_e32 v137, v202, v201
	v_max3_f32 v138, v136, v135, v138
	v_max3_f32 v132, v132, v137, v138
	v_mov_b32_e32 v137, v132
	v_sub_f32_e32 v170, v170, v171
	v_sub_f32_e32 v192, v192, v171
	v_sub_f32_e32 v193, v193, v171
	v_sub_f32_e32 v194, v235, v171
	s_waitcnt lgkmcnt(0)
	v_permlane16_swap_b32_e32 v137, v132
	v_max_f32_e32 v132, v132, v137
	v_mov_b32_e32 v137, v132
	v_sub_f32_e32 v195, v233, v171
	v_sub_f32_e32 v196, v234, v171
	v_sub_f32_e32 v198, v199, v171
	v_exp_f32_e32 v199, v170
	s_waitcnt lgkmcnt(0)
	v_permlane32_swap_b32_e32 v137, v132
	v_max_f32_e32 v132, v132, v137
	v_add_f32_e32 v137, 0x41000000, v204
	v_sub_f32_e32 v170, v232, v171
	v_cmp_gt_f32_e32 vcc, v132, v137
	v_exp_f32_e32 v192, v192
	v_exp_f32_e32 v193, v193
	v_exp_f32_e32 v194, v194
	v_exp_f32_e32 v195, v195
	v_exp_f32_e32 v196, v196
	v_exp_f32_e32 v198, v198
	v_exp_f32_e32 v200, v170
	s_cmp_eq_u64 vcc, 0
	v_max_f32_e32 v137, v204, v204
	s_cselect_b64 vcc, -1, 0
	v_max_f32_e32 v132, v137, v132
	v_cndmask_b32_e32 v170, v132, v204, vcc
	v_sub_f32_e32 v132, v204, v170
	v_cvt_pk_bf16_f32 v232, v192, v193
	v_cvt_pk_bf16_f32 v233, v194, v195
	v_cvt_pk_bf16_f32 v234, v196, v198
	v_cvt_pk_bf16_f32 v235, v199, v200
	v_exp_f32_e32 v132, v132
	s_nop 0
	v_mfma_f32_16x16x32_bf16 v[76:79], v[128:131], v[232:235], v[76:79]
	v_cmp_neq_f32_e32 vcc, 1.0, v132
	v_mfma_f32_16x16x32_bf16 v[72:75], v[124:127], v[232:235], v[72:75]
	v_mfma_f32_16x16x32_bf16 v[64:67], v[120:123], v[232:235], v[64:67]
	v_mfma_f32_16x16x32_bf16 v[60:63], v[116:119], v[232:235], v[60:63]
	v_mfma_f32_16x16x32_bf16 v[56:59], v[112:115], v[232:235], v[56:59]
	v_mfma_f32_16x16x32_bf16 v[52:55], v[104:107], v[232:235], v[52:55]
	v_mfma_f32_16x16x32_bf16 v[48:51], v[108:111], v[232:235], v[48:51]
	v_mfma_f32_16x16x32_bf16 v[40:43], v[100:103], v[232:235], v[40:43]
	s_cbranch_vccz .LBB0_139
	v_pk_mul_f32 v[46:47], v[46:47], v[132:133] op_sel_hi:[1,0]
	v_pk_mul_f32 v[44:45], v[44:45], v[132:133] op_sel_hi:[1,0]
	v_pk_mul_f32 v[70:71], v[70:71], v[132:133] op_sel_hi:[1,0]
	v_pk_mul_f32 v[68:69], v[68:69], v[132:133] op_sel_hi:[1,0]
	v_pk_mul_f32 v[82:83], v[82:83], v[132:133] op_sel_hi:[1,0]
	v_pk_mul_f32 v[80:81], v[80:81], v[132:133] op_sel_hi:[1,0]
	v_pk_mul_f32 v[86:87], v[86:87], v[132:133] op_sel_hi:[1,0]
	v_pk_mul_f32 v[84:85], v[84:85], v[132:133] op_sel_hi:[1,0]
	v_pk_mul_f32 v[90:91], v[90:91], v[132:133] op_sel_hi:[1,0]
	v_pk_mul_f32 v[88:89], v[88:89], v[132:133] op_sel_hi:[1,0]
	v_pk_mul_f32 v[94:95], v[94:95], v[132:133] op_sel_hi:[1,0]
	v_pk_mul_f32 v[92:93], v[92:93], v[132:133] op_sel_hi:[1,0]
	v_pk_mul_f32 v[98:99], v[98:99], v[132:133] op_sel_hi:[1,0]
	v_pk_mul_f32 v[96:97], v[96:97], v[132:133] op_sel_hi:[1,0]
	v_pk_mul_f32 v[38:39], v[38:39], v[132:133] op_sel_hi:[1,0]
	v_pk_mul_f32 v[36:37], v[36:37], v[132:133] op_sel_hi:[1,0]
	s_branch .LBB0_139
